# rg3 carry chains: 32 AGG loads in flight instead of serialized per-chunk round trips
# speedup vs baseline: 1.0286x; 1.0286x over previous
.LBB0_800:
	s_and_b32 s0, s28, s13
	s_add_u32 s40, s62, 0x432000
	s_addc_u32 s41, s63, 0
	s_cmp_eq_u32 s71, 0
	s_cselect_b64 s[44:45], -1, 0
	v_lshlrev_b32_e32 v2, 3, v0
	s_lshl_b32 s4, s0, 13
	s_add_u32 s94, s40, s4
	s_addc_u32 s95, s41, 0
	s_movk_i32 s96, 0x2000
	s_mov_b32 s97, 0
	s_mov_b32 s92, s71
	s_mov_b32 s98, 0
.Lcarry_chain:
	s_cmp_eq_u32 s92, 0
	s_cbranch_scc1 .Lcarry_chain_done
.Lcarry_batch:
	s_cmp_ge_u32 s92, 32
	s_cbranch_scc1 .Lcarry_loads
	v_mov_b32_e32 v44, 1.0
	v_mov_b32_e32 v45, 0
	v_mov_b32_e32 v46, 1.0
	v_mov_b32_e32 v47, 0
	v_mov_b32_e32 v48, 1.0
	v_mov_b32_e32 v49, 0
	v_mov_b32_e32 v50, 1.0
	v_mov_b32_e32 v51, 0
	v_mov_b32_e32 v52, 1.0
	v_mov_b32_e32 v53, 0
	v_mov_b32_e32 v54, 1.0
	v_mov_b32_e32 v55, 0
	v_mov_b32_e32 v56, 1.0
	v_mov_b32_e32 v57, 0
	v_mov_b32_e32 v58, 1.0
	v_mov_b32_e32 v59, 0
	v_mov_b32_e32 v60, 1.0
	v_mov_b32_e32 v61, 0
	v_mov_b32_e32 v62, 1.0
	v_mov_b32_e32 v63, 0
	v_mov_b32_e32 v64, 1.0
	v_mov_b32_e32 v65, 0
	v_mov_b32_e32 v66, 1.0
	v_mov_b32_e32 v67, 0
	v_mov_b32_e32 v68, 1.0
	v_mov_b32_e32 v69, 0
	v_mov_b32_e32 v70, 1.0
	v_mov_b32_e32 v71, 0
	v_mov_b32_e32 v72, 1.0
	v_mov_b32_e32 v73, 0
	v_mov_b32_e32 v74, 1.0
	v_mov_b32_e32 v75, 0
	v_mov_b32_e32 v76, 1.0
	v_mov_b32_e32 v77, 0
	v_mov_b32_e32 v78, 1.0
	v_mov_b32_e32 v79, 0
	v_mov_b32_e32 v80, 1.0
	v_mov_b32_e32 v81, 0
	v_mov_b32_e32 v82, 1.0
	v_mov_b32_e32 v83, 0
	v_mov_b32_e32 v84, 1.0
	v_mov_b32_e32 v85, 0
	v_mov_b32_e32 v86, 1.0
	v_mov_b32_e32 v87, 0
	v_mov_b32_e32 v88, 1.0
	v_mov_b32_e32 v89, 0
	v_mov_b32_e32 v90, 1.0
	v_mov_b32_e32 v91, 0
	v_mov_b32_e32 v92, 1.0
	v_mov_b32_e32 v93, 0
	v_mov_b32_e32 v94, 1.0
	v_mov_b32_e32 v95, 0
	v_mov_b32_e32 v96, 1.0
	v_mov_b32_e32 v97, 0
	v_mov_b32_e32 v98, 1.0
	v_mov_b32_e32 v99, 0
	v_mov_b32_e32 v100, 1.0
	v_mov_b32_e32 v101, 0
	v_mov_b32_e32 v102, 1.0
	v_mov_b32_e32 v103, 0
	v_mov_b32_e32 v104, 1.0
	v_mov_b32_e32 v105, 0
	v_mov_b32_e32 v106, 1.0
	v_mov_b32_e32 v107, 0
.Lcarry_loads:
	global_load_dwordx2 v[44:45], v2, s[94:95]
	s_add_u32 s94, s94, s96
	s_addc_u32 s95, s95, s97
	s_cmp_le_u32 s92, 1
	s_cbranch_scc1 .Lcarry_issued
	global_load_dwordx2 v[46:47], v2, s[94:95]
	s_add_u32 s94, s94, s96
	s_addc_u32 s95, s95, s97
	s_cmp_le_u32 s92, 2
	s_cbranch_scc1 .Lcarry_issued
	global_load_dwordx2 v[48:49], v2, s[94:95]
	s_add_u32 s94, s94, s96
	s_addc_u32 s95, s95, s97
	s_cmp_le_u32 s92, 3
	s_cbranch_scc1 .Lcarry_issued
	global_load_dwordx2 v[50:51], v2, s[94:95]
	s_add_u32 s94, s94, s96
	s_addc_u32 s95, s95, s97
	s_cmp_le_u32 s92, 4
	s_cbranch_scc1 .Lcarry_issued
	global_load_dwordx2 v[52:53], v2, s[94:95]
	s_add_u32 s94, s94, s96
	s_addc_u32 s95, s95, s97
	s_cmp_le_u32 s92, 5
	s_cbranch_scc1 .Lcarry_issued
	global_load_dwordx2 v[54:55], v2, s[94:95]
	s_add_u32 s94, s94, s96
	s_addc_u32 s95, s95, s97
	s_cmp_le_u32 s92, 6
	s_cbranch_scc1 .Lcarry_issued
	global_load_dwordx2 v[56:57], v2, s[94:95]
	s_add_u32 s94, s94, s96
	s_addc_u32 s95, s95, s97
	s_cmp_le_u32 s92, 7
	s_cbranch_scc1 .Lcarry_issued
	global_load_dwordx2 v[58:59], v2, s[94:95]
	s_add_u32 s94, s94, s96
	s_addc_u32 s95, s95, s97
	s_cmp_le_u32 s92, 8
	s_cbranch_scc1 .Lcarry_issued
	global_load_dwordx2 v[60:61], v2, s[94:95]
	s_add_u32 s94, s94, s96
	s_addc_u32 s95, s95, s97
	s_cmp_le_u32 s92, 9
	s_cbranch_scc1 .Lcarry_issued
	global_load_dwordx2 v[62:63], v2, s[94:95]
	s_add_u32 s94, s94, s96
	s_addc_u32 s95, s95, s97
	s_cmp_le_u32 s92, 10
	s_cbranch_scc1 .Lcarry_issued
	global_load_dwordx2 v[64:65], v2, s[94:95]
	s_add_u32 s94, s94, s96
	s_addc_u32 s95, s95, s97
	s_cmp_le_u32 s92, 11
	s_cbranch_scc1 .Lcarry_issued
	global_load_dwordx2 v[66:67], v2, s[94:95]
	s_add_u32 s94, s94, s96
	s_addc_u32 s95, s95, s97
	s_cmp_le_u32 s92, 12
	s_cbranch_scc1 .Lcarry_issued
	global_load_dwordx2 v[68:69], v2, s[94:95]
	s_add_u32 s94, s94, s96
	s_addc_u32 s95, s95, s97
	s_cmp_le_u32 s92, 13
	s_cbranch_scc1 .Lcarry_issued
	global_load_dwordx2 v[70:71], v2, s[94:95]
	s_add_u32 s94, s94, s96
	s_addc_u32 s95, s95, s97
	s_cmp_le_u32 s92, 14
	s_cbranch_scc1 .Lcarry_issued
	global_load_dwordx2 v[72:73], v2, s[94:95]
	s_add_u32 s94, s94, s96
	s_addc_u32 s95, s95, s97
	s_cmp_le_u32 s92, 15
	s_cbranch_scc1 .Lcarry_issued
	global_load_dwordx2 v[74:75], v2, s[94:95]
	s_add_u32 s94, s94, s96
	s_addc_u32 s95, s95, s97
	s_cmp_le_u32 s92, 16
	s_cbranch_scc1 .Lcarry_issued
	global_load_dwordx2 v[76:77], v2, s[94:95]
	s_add_u32 s94, s94, s96
	s_addc_u32 s95, s95, s97
	s_cmp_le_u32 s92, 17
	s_cbranch_scc1 .Lcarry_issued
	global_load_dwordx2 v[78:79], v2, s[94:95]
	s_add_u32 s94, s94, s96
	s_addc_u32 s95, s95, s97
	s_cmp_le_u32 s92, 18
	s_cbranch_scc1 .Lcarry_issued
	global_load_dwordx2 v[80:81], v2, s[94:95]
	s_add_u32 s94, s94, s96
	s_addc_u32 s95, s95, s97
	s_cmp_le_u32 s92, 19
	s_cbranch_scc1 .Lcarry_issued
	global_load_dwordx2 v[82:83], v2, s[94:95]
	s_add_u32 s94, s94, s96
	s_addc_u32 s95, s95, s97
	s_cmp_le_u32 s92, 20
	s_cbranch_scc1 .Lcarry_issued
	global_load_dwordx2 v[84:85], v2, s[94:95]
	s_add_u32 s94, s94, s96
	s_addc_u32 s95, s95, s97
	s_cmp_le_u32 s92, 21
	s_cbranch_scc1 .Lcarry_issued
	global_load_dwordx2 v[86:87], v2, s[94:95]
	s_add_u32 s94, s94, s96
	s_addc_u32 s95, s95, s97
	s_cmp_le_u32 s92, 22
	s_cbranch_scc1 .Lcarry_issued
	global_load_dwordx2 v[88:89], v2, s[94:95]
	s_add_u32 s94, s94, s96
	s_addc_u32 s95, s95, s97
	s_cmp_le_u32 s92, 23
	s_cbranch_scc1 .Lcarry_issued
	global_load_dwordx2 v[90:91], v2, s[94:95]
	s_add_u32 s94, s94, s96
	s_addc_u32 s95, s95, s97
	s_cmp_le_u32 s92, 24
	s_cbranch_scc1 .Lcarry_issued
	global_load_dwordx2 v[92:93], v2, s[94:95]
	s_add_u32 s94, s94, s96
	s_addc_u32 s95, s95, s97
	s_cmp_le_u32 s92, 25
	s_cbranch_scc1 .Lcarry_issued
	global_load_dwordx2 v[94:95], v2, s[94:95]
	s_add_u32 s94, s94, s96
	s_addc_u32 s95, s95, s97
	s_cmp_le_u32 s92, 26
	s_cbranch_scc1 .Lcarry_issued
	global_load_dwordx2 v[96:97], v2, s[94:95]
	s_add_u32 s94, s94, s96
	s_addc_u32 s95, s95, s97
	s_cmp_le_u32 s92, 27
	s_cbranch_scc1 .Lcarry_issued
	global_load_dwordx2 v[98:99], v2, s[94:95]
	s_add_u32 s94, s94, s96
	s_addc_u32 s95, s95, s97
	s_cmp_le_u32 s92, 28
	s_cbranch_scc1 .Lcarry_issued
	global_load_dwordx2 v[100:101], v2, s[94:95]
	s_add_u32 s94, s94, s96
	s_addc_u32 s95, s95, s97
	s_cmp_le_u32 s92, 29
	s_cbranch_scc1 .Lcarry_issued
	global_load_dwordx2 v[102:103], v2, s[94:95]
	s_add_u32 s94, s94, s96
	s_addc_u32 s95, s95, s97
	s_cmp_le_u32 s92, 30
	s_cbranch_scc1 .Lcarry_issued
	global_load_dwordx2 v[104:105], v2, s[94:95]
	s_add_u32 s94, s94, s96
	s_addc_u32 s95, s95, s97
	s_cmp_le_u32 s92, 31
	s_cbranch_scc1 .Lcarry_issued
	global_load_dwordx2 v[106:107], v2, s[94:95]
	s_add_u32 s94, s94, s96
	s_addc_u32 s95, s95, s97
.Lcarry_issued:
	s_min_u32 s93, s92, 32
	s_sub_u32 s92, s92, s93
	s_cmp_ge_u32 s93, 32
	s_cbranch_scc1 .Lcarry_consume
	s_waitcnt vmcnt(0)
.Lcarry_consume:
	s_waitcnt vmcnt(31)
	v_fmac_f32_e32 v45, v113, v44
	s_waitcnt vmcnt(30)
	v_fmac_f32_e32 v47, v45, v46
	s_waitcnt vmcnt(29)
	v_fmac_f32_e32 v49, v47, v48
	s_waitcnt vmcnt(28)
	v_fmac_f32_e32 v51, v49, v50
	s_waitcnt vmcnt(27)
	v_fmac_f32_e32 v53, v51, v52
	s_waitcnt vmcnt(26)
	v_fmac_f32_e32 v55, v53, v54
	s_waitcnt vmcnt(25)
	v_fmac_f32_e32 v57, v55, v56
	s_waitcnt vmcnt(24)
	v_fmac_f32_e32 v59, v57, v58
	s_waitcnt vmcnt(23)
	v_fmac_f32_e32 v61, v59, v60
	s_waitcnt vmcnt(22)
	v_fmac_f32_e32 v63, v61, v62
	s_waitcnt vmcnt(21)
	v_fmac_f32_e32 v65, v63, v64
	s_waitcnt vmcnt(20)
	v_fmac_f32_e32 v67, v65, v66
	s_waitcnt vmcnt(19)
	v_fmac_f32_e32 v69, v67, v68
	s_waitcnt vmcnt(18)
	v_fmac_f32_e32 v71, v69, v70
	s_waitcnt vmcnt(17)
	v_fmac_f32_e32 v73, v71, v72
	s_waitcnt vmcnt(16)
	v_fmac_f32_e32 v75, v73, v74
	s_waitcnt vmcnt(15)
	v_fmac_f32_e32 v77, v75, v76
	s_waitcnt vmcnt(14)
	v_fmac_f32_e32 v79, v77, v78
	s_waitcnt vmcnt(13)
	v_fmac_f32_e32 v81, v79, v80
	s_waitcnt vmcnt(12)
	v_fmac_f32_e32 v83, v81, v82
	s_waitcnt vmcnt(11)
	v_fmac_f32_e32 v85, v83, v84
	s_waitcnt vmcnt(10)
	v_fmac_f32_e32 v87, v85, v86
	s_waitcnt vmcnt(9)
	v_fmac_f32_e32 v89, v87, v88
	s_waitcnt vmcnt(8)
	v_fmac_f32_e32 v91, v89, v90
	s_waitcnt vmcnt(7)
	v_fmac_f32_e32 v93, v91, v92
	s_waitcnt vmcnt(6)
	v_fmac_f32_e32 v95, v93, v94
	s_waitcnt vmcnt(5)
	v_fmac_f32_e32 v97, v95, v96
	s_waitcnt vmcnt(4)
	v_fmac_f32_e32 v99, v97, v98
	s_waitcnt vmcnt(3)
	v_fmac_f32_e32 v101, v99, v100
	s_waitcnt vmcnt(2)
	v_fmac_f32_e32 v103, v101, v102
	s_waitcnt vmcnt(1)
	v_fmac_f32_e32 v105, v103, v104
	s_waitcnt vmcnt(0)
	v_fmac_f32_e32 v107, v105, v106
	v_mov_b32_e32 v113, v107
	s_cmp_lg_u32 s92, 0
	s_cbranch_scc1 .Lcarry_batch
.Lcarry_chain_done:
	s_cmp_lg_u32 s98, 0
	s_cbranch_scc1 .Lcarry_all_done
	s_waitcnt vmcnt(0)
	v_swap_b32 v113, v115
	s_mov_b32 s98, 1
	s_sub_u32 s92, s70, s71
	s_add_u32 s4, s0, s70
	s_lshl_b32 s4, s4, 13
	s_add_u32 s94, s40, s4
	s_addc_u32 s95, s41, 0
	s_add_u32 s94, s94, 0x1000
	s_addc_u32 s95, s95, 0
	s_mov_b32 s96, 0xffffe000
	s_mov_b32 s97, -1
	s_branch .Lcarry_chain
.Lcarry_all_done:
	v_swap_b32 v113, v115
	s_and_b32 s28, s51, 0xffffffc0
	v_and_b32_e32 v112, 63, v36
	s_branch .LBB0_819

.LBB0_815:
	s_waitcnt vmcnt(4)
	v_lshl_add_u32 v0, v41, 10, v43
	ds_write_b128 v0, v[8:11]
	s_or_b64 exec, exec, s[0:1]
	s_and_saveexec_b64 s[0:1], s[46:47]
	s_cbranch_execnz .LBB0_795
	s_branch .LBB0_796
.LBB0_819:
	s_ashr_i32 s13, s51, 6
	s_mul_i32 s0, s13, 0x1200
	s_add_i32 s4, s0, 0
	s_add_i32 s4, s4, 0x18c00
	s_add_u32 s0, s62, s54
	s_addc_u32 s1, s63, s55
	s_load_dwordx4 s[40:43], s[64:65], 0x50
	s_add_u32 s0, s0, 0x4000
	s_addc_u32 s1, s1, 0
	s_add_u32 s38, s38, s60
	s_addc_u32 s39, s39, s61
	s_waitcnt lgkmcnt(0)
	s_add_u32 s40, s40, s60
	s_addc_u32 s41, s41, s61
	v_lshl_add_u64 v[6:7], v[0:1], 2, s[40:41]
	v_add_co_u32_e32 v6, vcc, s3, v6
	v_add_u32_e32 v10, s58, v0
	v_mov_b32_e32 v2, s42
	v_mov_b32_e32 v3, s43
	v_lshl_add_u64 v[4:5], v[0:1], 2, s[40:41]
	v_addc_co_u32_e32 v7, vcc, 0, v7, vcc
	v_ashrrev_i32_e32 v11, 31, v10
	v_add_co_u32_e32 v8, vcc, s3, v4
	v_lshl_add_u64 v[2:3], v[10:11], 2, v[2:3]
	s_nop 0
	v_addc_co_u32_e32 v9, vcc, 0, v5, vcc
	global_load_dword v114, v[2:3], off
	global_load_dword v122, v[4:5], off
	global_load_dword v123, v[4:5], off offset:2048
	global_load_dword v124, v[6:7], off
	global_load_dword v125, v[8:9], off offset:2048
	v_lshl_add_u32 v0, v0, 1, 0
	s_barrier
	ds_read_u16 v1, v0
	ds_read_u16 v5, v0 offset:1024
	ds_read_u16 v6, v0 offset:2048
	ds_read_u16 v7, v0 offset:3072
	v_lshl_add_u32 v17, v112, 1, s4
	s_waitcnt lgkmcnt(3)
	v_lshlrev_b32_e32 v1, 16, v1
	s_waitcnt lgkmcnt(2)
	v_lshlrev_b32_e32 v5, 16, v5
	s_waitcnt lgkmcnt(1)
	v_lshlrev_b32_e32 v6, 16, v6
	s_waitcnt lgkmcnt(0)
	v_lshlrev_b32_e32 v7, 16, v7
	v_and_b32_e32 v172, 48, v112
	v_lshl_add_u64 v[2:3], s[62:63], 0, v[172:173]
	s_mov_b64 s[40:41], 0x3f2000
	v_lshl_add_u64 v[116:117], v[2:3], 0, s[40:41]
	v_and_b32_e32 v16, 15, v36
	s_add_i32 s29, s28, 0x600
	v_or_b32_e32 v4, s28, v16
	s_add_i32 s5, s28, 0x200
	s_add_i32 s26, s28, 0x400
	v_add_u32_e32 v126, s28, v16
	v_and_b32_e32 v127, 64, v212
	s_mov_b32 s35, 0
	s_waitcnt vmcnt(3)
	v_fma_f32 v1, v122, v1, v114
	s_waitcnt vmcnt(2)
	v_fmac_f32_e32 v1, v123, v5
	s_waitcnt vmcnt(1)
	v_fmac_f32_e32 v1, v124, v6
	s_waitcnt vmcnt(0)
	v_fmac_f32_e32 v1, v125, v7
	v_bfe_u32 v8, v1, 16, 1
	v_add3_u32 v1, v1, v8, s33
	ds_write_b16_d16_hi v17, v1
	ds_read_u16 v1, v0 offset:4096
	v_fma_f32 v2, v122, v5, v114
	v_fmac_f32_e32 v2, v123, v6
	v_fmac_f32_e32 v2, v124, v7
	v_fma_f32 v5, v122, v6, v114
	s_waitcnt lgkmcnt(0)
	v_lshlrev_b32_e32 v1, 16, v1
	v_fmac_f32_e32 v2, v125, v1
	v_bfe_u32 v3, v2, 16, 1
	v_add3_u32 v2, v2, v3, s33
	ds_write_b16_d16_hi v17, v2 offset:144
	ds_read_u16 v3, v0 offset:5120
	v_fmac_f32_e32 v5, v123, v7
	v_fmac_f32_e32 v5, v124, v1
	v_fma_f32 v7, v122, v7, v114
	v_fmac_f32_e32 v7, v123, v1
	s_waitcnt lgkmcnt(0)
	v_lshlrev_b32_e32 v3, 16, v3
	v_fmac_f32_e32 v5, v125, v3
	v_bfe_u32 v6, v5, 16, 1
	v_add3_u32 v5, v5, v6, s33
	ds_write_b16_d16_hi v17, v5 offset:288
	ds_read_u16 v6, v0 offset:6144
	v_fmac_f32_e32 v7, v124, v3
	v_fma_f32 v1, v122, v1, v114
	v_fmac_f32_e32 v1, v123, v3
	v_fma_f32 v3, v122, v3, v114
	s_waitcnt lgkmcnt(0)
	v_lshlrev_b32_e32 v9, 16, v6
	v_fmac_f32_e32 v7, v125, v9
	v_bfe_u32 v6, v7, 16, 1
	v_add3_u32 v6, v7, v6, s33
	ds_write_b16_d16_hi v17, v6 offset:432
	ds_read_u16 v7, v0 offset:7168
	v_fmac_f32_e32 v1, v124, v9
	v_fmac_f32_e32 v3, v123, v9
	v_fma_f32 v9, v122, v9, v114
	v_ashrrev_i32_e32 v5, 31, v4
	s_waitcnt lgkmcnt(0)
	v_lshlrev_b32_e32 v7, 16, v7
	v_fmac_f32_e32 v1, v125, v7
	v_bfe_u32 v8, v1, 16, 1
	v_add3_u32 v1, v1, v8, s33
	ds_write_b16_d16_hi v17, v1 offset:576
	ds_read_u16 v1, v0 offset:8192
	v_fmac_f32_e32 v3, v124, v7
	v_fmac_f32_e32 v9, v123, v7
	v_fma_f32 v7, v122, v7, v114
	v_add_u32_e32 v2, 0x200, v126
	s_waitcnt lgkmcnt(0)
	v_lshlrev_b32_e32 v1, 16, v1
	v_fmac_f32_e32 v3, v125, v1
	v_bfe_u32 v10, v3, 16, 1
	v_add3_u32 v3, v3, v10, s33
	ds_write_b16_d16_hi v17, v3 offset:720
	ds_read_u16 v3, v0 offset:9216
	v_fmac_f32_e32 v9, v124, v1
	v_fmac_f32_e32 v7, v123, v1
	v_fma_f32 v1, v122, v1, v114
	v_add_u32_e32 v6, 0x400, v4
	s_waitcnt lgkmcnt(0)
	v_lshlrev_b32_e32 v12, 16, v3
	v_fmac_f32_e32 v9, v125, v12
	v_bfe_u32 v3, v9, 16, 1
	v_add3_u32 v3, v9, v3, s33
	ds_write_b16_d16_hi v17, v3 offset:864
	ds_read_u16 v3, v0 offset:10240
	v_fmac_f32_e32 v7, v124, v12
	v_fmac_f32_e32 v1, v123, v12
	v_fma_f32 v9, v122, v12, v114
	v_add_u32_e32 v8, 0x600, v126
	s_waitcnt lgkmcnt(0)
	v_lshlrev_b32_e32 v13, 16, v3
	v_fmac_f32_e32 v7, v125, v13
	v_bfe_u32 v3, v7, 16, 1
	v_add3_u32 v3, v7, v3, s33
	ds_write_b16_d16_hi v17, v3 offset:1008
	ds_read_u16 v7, v0 offset:11264
	v_fmac_f32_e32 v1, v124, v13
	v_fmac_f32_e32 v9, v123, v13
	v_fma_f32 v13, v122, v13, v114
	v_lshlrev_b64 v[10:11], 7, v[4:5]
	s_waitcnt lgkmcnt(0)
	v_lshlrev_b32_e32 v14, 16, v7
	v_fmac_f32_e32 v1, v125, v14
	v_bfe_u32 v7, v1, 16, 1
	v_add3_u32 v1, v1, v7, s33
	ds_write_b16_d16_hi v17, v1 offset:1152
	ds_read_u16 v1, v0 offset:12288
	v_fmac_f32_e32 v9, v124, v14
	v_fmac_f32_e32 v13, v123, v14
	v_lshlrev_b64 v[4:5], 2, v[4:5]
	v_ashrrev_i32_e32 v3, 31, v2
	s_waitcnt lgkmcnt(0)
	v_lshlrev_b32_e32 v1, 16, v1
	v_fmac_f32_e32 v9, v125, v1
	v_bfe_u32 v12, v9, 16, 1
	v_add3_u32 v9, v9, v12, s33
	ds_write_b16_d16_hi v17, v9 offset:1296
	ds_read_u16 v12, v0 offset:13312
	v_fmac_f32_e32 v13, v124, v1
	v_ashrrev_i32_e32 v7, 31, v6
	v_ashrrev_i32_e32 v9, 31, v8
	v_lshl_add_u64 v[10:11], v[116:117], 0, v[10:11]
	s_waitcnt lgkmcnt(0)
	v_lshlrev_b32_e32 v15, 16, v12
	v_fmac_f32_e32 v13, v125, v15
	v_bfe_u32 v12, v13, 16, 1
	v_add3_u32 v12, v13, v12, s33
	ds_write_b16_d16_hi v17, v12 offset:1440
	ds_read_u16 v12, v0 offset:14336
	v_fma_f32 v13, v122, v14, v114
	v_fmac_f32_e32 v13, v123, v1
	v_fmac_f32_e32 v13, v124, v15
	v_fma_f32 v1, v122, v1, v114
	s_waitcnt lgkmcnt(0)
	v_lshlrev_b32_e32 v14, 16, v12
	v_fmac_f32_e32 v13, v125, v14
	v_bfe_u32 v12, v13, 16, 1
	v_add3_u32 v12, v13, v12, s33
	ds_write_b16_d16_hi v17, v12 offset:1584
	ds_read_u16 v18, v0 offset:15360
	v_fmac_f32_e32 v1, v123, v15
	v_fmac_f32_e32 v1, v124, v14
	v_fma_f32 v15, v122, v15, v114
	v_fmac_f32_e32 v15, v123, v14
	s_waitcnt lgkmcnt(0)
	v_lshlrev_b32_e32 v18, 16, v18
	v_fmac_f32_e32 v1, v125, v18
	v_bfe_u32 v19, v1, 16, 1
	v_add3_u32 v1, v1, v19, s33
	ds_write_b16_d16_hi v17, v1 offset:1728
	ds_read_u16 v1, v0 offset:16384
	v_fmac_f32_e32 v15, v124, v18
	v_fma_f32 v14, v122, v14, v114
	v_fmac_f32_e32 v14, v123, v18
	v_fma_f32 v18, v122, v18, v114
	s_waitcnt lgkmcnt(0)
	v_lshlrev_b32_e32 v1, 16, v1
	v_fmac_f32_e32 v15, v125, v1
	v_bfe_u32 v19, v15, 16, 1
	v_add3_u32 v15, v15, v19, s33
	ds_write_b16_d16_hi v17, v15 offset:1872
	ds_read_u16 v15, v0 offset:17408
	v_fmac_f32_e32 v14, v124, v1
	v_fmac_f32_e32 v18, v123, v1
	v_fma_f32 v1, v122, v1, v114
	v_lshl_add_u64 v[12:13], s[0:1], 0, v[4:5]
	s_waitcnt lgkmcnt(0)
	v_lshlrev_b32_e32 v15, 16, v15
	v_fmac_f32_e32 v14, v125, v15
	v_bfe_u32 v19, v14, 16, 1
	v_add3_u32 v14, v14, v19, s33
	ds_write_b16_d16_hi v17, v14 offset:2016
	ds_read_u16 v14, v0 offset:18432
	v_fmac_f32_e32 v18, v124, v15
	v_fmac_f32_e32 v1, v123, v15
	v_fma_f32 v15, v122, v15, v114
	v_lshl_add_u64 v[4:5], s[38:39], 0, v[4:5]
	s_waitcnt lgkmcnt(0)
	v_lshlrev_b32_e32 v14, 16, v14
	v_fmac_f32_e32 v18, v125, v14
	v_bfe_u32 v19, v18, 16, 1
	v_add3_u32 v18, v18, v19, s33
	ds_write_b16_d16_hi v17, v18 offset:2160
	ds_read_u16 v18, v0 offset:19456
	v_fmac_f32_e32 v1, v124, v14
	v_fmac_f32_e32 v15, v123, v14
	v_fma_f32 v14, v122, v14, v114
	v_lshl_add_u64 v[2:3], v[2:3], 2, s[38:39]
	s_waitcnt lgkmcnt(0)
	v_lshlrev_b32_e32 v18, 16, v18
	v_fmac_f32_e32 v1, v125, v18
	v_bfe_u32 v19, v1, 16, 1
	v_add3_u32 v1, v1, v19, s33
	ds_write_b16_d16_hi v17, v1 offset:2304
	ds_read_u16 v1, v0 offset:20480
	v_fmac_f32_e32 v15, v124, v18
	v_fmac_f32_e32 v14, v123, v18
	v_fma_f32 v18, v122, v18, v114
	v_lshl_add_u64 v[6:7], v[6:7], 2, s[38:39]
	s_waitcnt lgkmcnt(0)
	v_lshlrev_b32_e32 v1, 16, v1
	v_fmac_f32_e32 v15, v125, v1
	v_bfe_u32 v19, v15, 16, 1
	v_add3_u32 v15, v15, v19, s33
	ds_write_b16_d16_hi v17, v15 offset:2448
	ds_read_u16 v15, v0 offset:21504
	v_fmac_f32_e32 v14, v124, v1
	v_fmac_f32_e32 v18, v123, v1
	v_fma_f32 v1, v122, v1, v114
	v_lshl_add_u64 v[8:9], v[8:9], 2, s[38:39]
	s_waitcnt lgkmcnt(0)
	v_lshlrev_b32_e32 v15, 16, v15
	v_fmac_f32_e32 v14, v125, v15
	v_bfe_u32 v19, v14, 16, 1
	v_add3_u32 v14, v14, v19, s33
	ds_write_b16_d16_hi v17, v14 offset:2592
	ds_read_u16 v14, v0 offset:22528
	v_fmac_f32_e32 v18, v124, v15
	v_fmac_f32_e32 v1, v123, v15
	v_fma_f32 v15, v122, v15, v114
	s_waitcnt lgkmcnt(0)
	v_lshlrev_b32_e32 v19, 16, v14
	v_fmac_f32_e32 v18, v125, v19
	v_bfe_u32 v14, v18, 16, 1
	v_add3_u32 v14, v18, v14, s33
	ds_write_b16_d16_hi v17, v14 offset:2736
	ds_read_u16 v18, v0 offset:23552
	v_fmac_f32_e32 v1, v124, v19
	v_fmac_f32_e32 v15, v123, v19
	v_fma_f32 v19, v122, v19, v114
	v_or_b32_e32 v14, s5, v16
	s_waitcnt lgkmcnt(0)
	v_lshlrev_b32_e32 v21, 16, v18
	v_fmac_f32_e32 v1, v125, v21
	v_bfe_u32 v18, v1, 16, 1
	v_add3_u32 v1, v1, v18, s33
	ds_write_b16_d16_hi v17, v1 offset:2880
	ds_read_u16 v1, v0 offset:24576
	v_fmac_f32_e32 v15, v124, v21
	v_fmac_f32_e32 v19, v123, v21
	v_fma_f32 v21, v122, v21, v114
	v_or_b32_e32 v18, s26, v16
	s_waitcnt lgkmcnt(0)
	v_lshlrev_b32_e32 v1, 16, v1
	v_fmac_f32_e32 v15, v125, v1
	v_bfe_u32 v20, v15, 16, 1
	v_add3_u32 v15, v15, v20, s33
	ds_write_b16_d16_hi v17, v15 offset:3024
	ds_read_u16 v15, v0 offset:25600
	v_fmac_f32_e32 v19, v124, v1
	v_fmac_f32_e32 v21, v123, v1
	v_fma_f32 v1, v122, v1, v114
	v_or_b32_e32 v20, s29, v16
	s_waitcnt lgkmcnt(0)
	v_lshlrev_b32_e32 v22, 16, v15
	v_fmac_f32_e32 v19, v125, v22
	v_bfe_u32 v15, v19, 16, 1
	v_add3_u32 v15, v19, v15, s33
	ds_write_b16_d16_hi v17, v15 offset:3168
	ds_read_u16 v19, v0 offset:26624
	v_fmac_f32_e32 v21, v124, v22
	v_fmac_f32_e32 v1, v123, v22
	v_fma_f32 v22, v122, v22, v114
	v_ashrrev_i32_e32 v15, 31, v14
	s_waitcnt lgkmcnt(0)
	v_lshlrev_b32_e32 v23, 16, v19
	v_fmac_f32_e32 v21, v125, v23
	v_bfe_u32 v19, v21, 16, 1
	v_add3_u32 v19, v21, v19, s33
	ds_write_b16_d16_hi v17, v19 offset:3312
	ds_read_u16 v21, v0 offset:27648
	v_fmac_f32_e32 v1, v124, v23
	v_fmac_f32_e32 v22, v123, v23
	v_fma_f32 v23, v122, v23, v114
	v_ashrrev_i32_e32 v19, 31, v18
	s_waitcnt lgkmcnt(0)
	v_lshlrev_b32_e32 v24, 16, v21
	v_fmac_f32_e32 v1, v125, v24
	v_bfe_u32 v21, v1, 16, 1
	v_add3_u32 v1, v1, v21, s33
	ds_write_b16_d16_hi v17, v1 offset:3456
	ds_read_u16 v1, v0 offset:28672
	v_fmac_f32_e32 v22, v124, v24
	v_fmac_f32_e32 v23, v123, v24
	v_fma_f32 v24, v122, v24, v114
	v_ashrrev_i32_e32 v21, 31, v20
	s_waitcnt lgkmcnt(0)
	v_lshlrev_b32_e32 v1, 16, v1
	v_fmac_f32_e32 v22, v125, v1
	v_bfe_u32 v25, v22, 16, 1
	v_add3_u32 v22, v22, v25, s33
	ds_write_b16_d16_hi v17, v22 offset:3600
	ds_read_u16 v22, v0 offset:29696
	v_fmac_f32_e32 v23, v124, v1
	v_fmac_f32_e32 v24, v123, v1
	v_fma_f32 v1, v122, v1, v114
	v_lshlrev_b64 v[20:21], 7, v[20:21]
	s_waitcnt lgkmcnt(0)
	v_lshlrev_b32_e32 v22, 16, v22
	v_fmac_f32_e32 v23, v125, v22
	v_bfe_u32 v25, v23, 16, 1
	v_add3_u32 v23, v23, v25, s33
	ds_write_b16_d16_hi v17, v23 offset:3744
	ds_read_u16 v23, v0 offset:30720
	v_fmac_f32_e32 v24, v124, v22
	v_fmac_f32_e32 v1, v123, v22
	v_fma_f32 v22, v122, v22, v114
	v_lshlrev_b64 v[14:15], 7, v[14:15]
	s_waitcnt lgkmcnt(0)
	v_lshlrev_b32_e32 v23, 16, v23
	v_fmac_f32_e32 v24, v125, v23
	v_bfe_u32 v25, v24, 16, 1
	v_add3_u32 v24, v24, v25, s33
	ds_write_b16_d16_hi v17, v24 offset:3888
	ds_read_u16 v24, v0 offset:31744
	v_fmac_f32_e32 v1, v124, v23
	v_fmac_f32_e32 v22, v123, v23
	v_lshlrev_b64 v[18:19], 7, v[18:19]
	v_lshl_add_u64 v[14:15], v[116:117], 0, v[14:15]
	s_waitcnt lgkmcnt(0)
	v_lshlrev_b32_e32 v24, 16, v24
	v_fmac_f32_e32 v1, v125, v24
	v_bfe_u32 v25, v1, 16, 1
	v_add3_u32 v1, v1, v25, s33
	ds_write_b16_d16_hi v17, v1 offset:4032
	ds_read_u16 v1, v0 offset:32768
	v_fmac_f32_e32 v22, v124, v24
	v_lshl_add_u64 v[18:19], v[116:117], 0, v[18:19]
	s_lshl_b32 s26, s57, 1
	s_and_b32 s26, s26, 62
	s_waitcnt lgkmcnt(0)
	v_lshlrev_b32_e32 v25, 16, v1
	v_fmac_f32_e32 v22, v125, v25
	v_bfe_u32 v1, v22, 16, 1
	v_add3_u32 v1, v22, v1, s33
	ds_write_b16_d16_hi v17, v1 offset:4176
	ds_read_u16 v1, v0 offset:33792
	v_fma_f32 v22, v122, v23, v114
	v_fmac_f32_e32 v22, v123, v24
	v_fmac_f32_e32 v22, v124, v25
	s_or_b32 s26, s26, s50
	s_waitcnt lgkmcnt(0)
	v_lshlrev_b32_e32 v23, 16, v1
	v_fmac_f32_e32 v22, v125, v23
	v_bfe_u32 v1, v22, 16, 1
	v_add3_u32 v1, v22, v1, s33
	ds_write_b16_d16_hi v17, v1 offset:4320
	ds_read_u16 v22, v0 offset:34816
	v_lshl_add_u64 v[0:1], v[116:117], 0, v[20:21]
	v_fma_f32 v20, v122, v24, v114
	v_fmac_f32_e32 v20, v123, v25
	v_fmac_f32_e32 v20, v124, v23
	s_waitcnt lgkmcnt(0)
	v_lshlrev_b32_e32 v21, 16, v22
	v_fmac_f32_e32 v20, v125, v21
	v_bfe_u32 v21, v20, 16, 1
	v_add3_u32 v20, v20, v21, s33
	ds_write_b16_d16_hi v17, v20 offset:4464
	s_waitcnt lgkmcnt(0)
	global_load_dwordx4 v[64:67], v[10:11], off
	global_load_dwordx4 v[72:75], v[10:11], off offset:64
	global_load_dwordx4 v[68:71], v[14:15], off
	global_load_dwordx4 v[76:79], v[14:15], off offset:64
	global_load_dword v96, v[4:5], off
	global_load_dword v95, v[2:3], off
	global_load_dwordx4 v[56:59], v[18:19], off offset:64
	global_load_dwordx4 v[52:55], v[0:1], off
	global_load_dwordx4 v[60:63], v[0:1], off offset:64
	global_load_dword v89, v[6:7], off
	global_load_dword v88, v[8:9], off
	global_load_dword v94, v[12:13], off
	global_load_dwordx4 v[48:51], v[18:19], off
	global_load_dword v87, v[12:13], off offset:2048
	v_and_b32_e32 v0, 48, v36
	v_mul_u32_u24_e32 v1, 0x90, v16
	v_add3_u32 v12, s4, v0, v1
	ds_read_b128 v[0:3], v12
	ds_read_b128 v[4:7], v12 offset:64
	ds_read_b128 v[8:11], v12 offset:2304
	ds_read_b128 v[12:15], v12 offset:2368
	s_load_dwordx2 s[4:5], s[64:65], 0x100
	s_lshl_b32 s26, s26, 10
	s_lshl_b64 s[40:41], s[26:27], 2
	v_lshrrev_b32_e32 v17, 4, v112
	v_xor_b32_e32 v18, 2, v17
	s_waitcnt lgkmcnt(0)
	s_add_u32 s26, s4, s40
	s_addc_u32 s29, s5, s41
	s_add_u32 s48, s26, 0x6000000
	s_addc_u32 s49, s29, 0
	s_cmp_lt_i32 s57, 32
	s_cselect_b64 s[46:47], -1, 0
	s_and_b64 s[46:47], s[44:45], s[46:47]
	v_cmp_gt_u32_e64 s[44:45], 16, v112
	s_and_b64 s[66:67], s[46:47], s[44:45]
	s_cmp_lg_u32 s71, s70
	s_cselect_b64 s[70:71], -1, 0
	s_lshl_b32 s26, s51, 1
	v_add_u32_e32 v19, 16, v36
	s_and_b32 s26, s26, 0xffffff80
	v_and_or_b32 v19, v19, 63, v127
	v_cmp_eq_u32_e64 s[40:41], 3, v17
	v_cmp_lt_u32_e64 s[42:43], 1, v18
	v_or_b32_e32 v18, v127, v16
	v_cmp_ne_u32_e32 vcc, 3, v17
	v_lshl_add_u32 v17, v17, 12, s26
	s_and_b32 s26, s57, 31
	v_lshlrev_b32_e32 v128, 2, v19
	v_or_b32_e32 v19, v127, v112
	v_lshlrev_b32_e32 v130, 2, v18
	v_add_u32_e32 v18, 48, v36
	s_lshl_b32 s26, s26, 11
	v_lshlrev_b32_e32 v19, 2, v19
	v_and_or_b32 v18, v18, 63, v127
	s_or_b64 s[70:71], vcc, s[70:71]
	s_ashr_i32 s29, s28, 31
	v_lshl_or_b32 v133, v16, 1, v17
	v_mov_b32_e32 v17, v173
	s_add_i32 s26, s56, s26
	v_xor_b32_e32 v129, 0x80, v19
	v_lshlrev_b32_e32 v131, 2, v18
	v_or_b32_e32 v132, 0xc0, v19
	s_nor_b64 s[68:69], s[70:71], s[68:69]
	v_lshl_add_u64 v[18:19], s[28:29], 0, v[16:17]
	s_lshl_b64 s[28:29], s[26:27], 2
	s_add_u32 s4, s4, s28
	s_addc_u32 s5, s5, s29
	v_lshl_add_u64 v[118:119], v[18:19], 2, s[4:5]
	v_lshlrev_b32_e32 v17, 2, v212
	v_lshlrev_b32_e32 v16, 2, v16
	s_movk_i32 s4, 0x100
	v_cmp_lt_u32_e64 s[46:47], 31, v112
	v_and_or_b32 v172, v17, s4, v16
	s_mov_b64 s[70:71], 0
	s_mov_b32 s26, 0
	v_readlane_b32 s51, v240, 36
	s_branch .LBB0_821
